# attention epilogues (FoX pair loop, band loops): neighbouring 8-column groups exchanged across half-waves with v_permlane32_swap and stored as 8 dwordx4 per lane instead of 16 dwordx2
# speedup vs baseline: 1.0379x; 1.0065x over previous
.Lband_epi_scale:
	v_pk_mul_f32 v[146:147], v[146:147], v[60:61] op_sel_hi:[1,0]
	v_pk_mul_f32 v[148:149], v[148:149], v[60:61] op_sel_hi:[1,0]
	v_pk_mul_f32 v[150:151], v[150:151], v[60:61] op_sel_hi:[1,0]
	v_pk_mul_f32 v[152:153], v[152:153], v[60:61] op_sel_hi:[1,0]
	v_pk_mul_f32 v[154:155], v[154:155], v[60:61] op_sel_hi:[1,0]
	v_pk_mul_f32 v[156:157], v[156:157], v[60:61] op_sel_hi:[1,0]
	v_pk_mul_f32 v[158:159], v[158:159], v[60:61] op_sel_hi:[1,0]
	v_pk_mul_f32 v[160:161], v[160:161], v[60:61] op_sel_hi:[1,0]
	v_pk_mul_f32 v[184:185], v[184:185], v[60:61] op_sel_hi:[1,0]
	v_pk_mul_f32 v[186:187], v[186:187], v[60:61] op_sel_hi:[1,0]
	v_pk_mul_f32 v[188:189], v[188:189], v[60:61] op_sel_hi:[1,0]
	v_pk_mul_f32 v[190:191], v[190:191], v[60:61] op_sel_hi:[1,0]
	v_pk_mul_f32 v[192:193], v[192:193], v[60:61] op_sel_hi:[1,0]
	v_pk_mul_f32 v[194:195], v[194:195], v[60:61] op_sel_hi:[1,0]
	v_pk_mul_f32 v[196:197], v[196:197], v[60:61] op_sel_hi:[1,0]
	v_pk_mul_f32 v[198:199], v[198:199], v[60:61] op_sel_hi:[1,0]
	v_lshl_add_u32 v62, v48, 3, v62
	v_cvt_pk_bf16_f32 v146, v146, v147
	v_cvt_pk_bf16_f32 v147, v148, v149
	v_cvt_pk_bf16_f32 v148, v150, v151
	v_cvt_pk_bf16_f32 v149, v152, v153
	s_nop 1
	v_permlane32_swap_b32_e32 v146, v148
	v_permlane32_swap_b32_e32 v147, v149
	global_store_dwordx4 v62, v[146:149], s[6:7]
	v_cvt_pk_bf16_f32 v154, v154, v155
	v_cvt_pk_bf16_f32 v155, v156, v157
	v_cvt_pk_bf16_f32 v156, v158, v159
	v_cvt_pk_bf16_f32 v157, v160, v161
	s_nop 1
	v_permlane32_swap_b32_e32 v154, v156
	v_permlane32_swap_b32_e32 v155, v157
	global_store_dwordx4 v62, v[154:157], s[6:7] offset:32
	v_cvt_pk_bf16_f32 v184, v184, v185
	v_cvt_pk_bf16_f32 v185, v186, v187
	v_cvt_pk_bf16_f32 v186, v188, v189
	v_cvt_pk_bf16_f32 v187, v190, v191
	s_nop 1
	v_permlane32_swap_b32_e32 v184, v186
	v_permlane32_swap_b32_e32 v185, v187
	global_store_dwordx4 v62, v[184:187], s[6:7] offset:64
	v_cvt_pk_bf16_f32 v192, v192, v193
	v_cvt_pk_bf16_f32 v193, v194, v195
	v_cvt_pk_bf16_f32 v194, v196, v197
	v_cvt_pk_bf16_f32 v195, v198, v199
	s_nop 1
	v_permlane32_swap_b32_e32 v192, v194
	v_permlane32_swap_b32_e32 v193, v195
	global_store_dwordx4 v62, v[192:195], s[6:7] offset:96
	s_add_i32 s0, s0, s68
	s_cmp_lt_u32 s0, 0x4000
	s_cbranch_scc1 .Lband_item
	v_lshlrev_b32_e32 v183, 2, v220
	v_add_u32_e32 v2, 0x10000, v183
	v_lshrrev_b32_e32 v183, 6, v220
	v_lshlrev_b32_e32 v183, 8, v183
	v_add_u32_e32 v183, 0x0, v183
	ds_read_b32 v2, v183 offset:0
	ds_read_b32 v3, v183 offset:4
	ds_read_b32 v4, v183 offset:8
	ds_read_b32 v5, v183 offset:12
	ds_read_b32 v6, v183 offset:16
	ds_read_b32 v7, v183 offset:20
	ds_read_b32 v8, v183 offset:24
	ds_read_b32 v9, v183 offset:28
	ds_read_b32 v10, v183 offset:32
	ds_read_b32 v11, v183 offset:36
	ds_read_b32 v12, v183 offset:40
	ds_read_b32 v13, v183 offset:44
	ds_read_b32 v14, v183 offset:48
	ds_read_b32 v15, v183 offset:52
	ds_read_b32 v16, v183 offset:56
	ds_read_b32 v17, v183 offset:60
	ds_read_b32 v18, v183 offset:64
	ds_read_b32 v19, v183 offset:68
	ds_read_b32 v20, v183 offset:72
	ds_read_b32 v21, v183 offset:76
	ds_read_b32 v22, v183 offset:80
	ds_read_b32 v23, v183 offset:84
	ds_read_b32 v24, v183 offset:88
	ds_read_b32 v25, v183 offset:92
	ds_read_b32 v26, v183 offset:96
	ds_read_b32 v27, v183 offset:100
	ds_read_b32 v28, v183 offset:104
	ds_read_b32 v29, v183 offset:108
	ds_read_b32 v30, v183 offset:112
	ds_read_b32 v31, v183 offset:116
	ds_read_b32 v32, v183 offset:120
	ds_read_b32 v33, v183 offset:124
	ds_read_b32 v34, v183 offset:128
	ds_read_b32 v35, v183 offset:132
	ds_read_b32 v36, v183 offset:136
	ds_read_b32 v37, v183 offset:140
	ds_read_b32 v38, v183 offset:144
	ds_read_b32 v39, v183 offset:148
	ds_read_b32 v40, v183 offset:152
	ds_read_b32 v41, v183 offset:156
	ds_read_b32 v42, v183 offset:160
	ds_read_b32 v43, v183 offset:164
	ds_read_b32 v44, v183 offset:168
	ds_read_b32 v45, v183 offset:172
	ds_read_b32 v46, v183 offset:176
	ds_read_b32 v47, v183 offset:180
	ds_read_b32 v48, v183 offset:184
	ds_read_b32 v49, v183 offset:188
	ds_read_b32 v50, v183 offset:192
	ds_read_b32 v51, v183 offset:196
	ds_read_b32 v52, v183 offset:200
	ds_read_b32 v53, v183 offset:204
	ds_read_b32 v54, v183 offset:208
	s_waitcnt lgkmcnt(0)
	v_readfirstlane_b32 s52, v54
	s_nop 3
	s_mov_b32 m0, s52
	v_readfirstlane_b32 s2, v2
	v_readfirstlane_b32 s3, v3
	v_readfirstlane_b32 s4, v4
	v_readfirstlane_b32 s5, v5
	v_readfirstlane_b32 s6, v6
	v_readfirstlane_b32 s7, v7
	v_readfirstlane_b32 s8, v8
	v_readfirstlane_b32 s9, v9
	v_readfirstlane_b32 s10, v10
	v_readfirstlane_b32 s11, v11
	v_readfirstlane_b32 s12, v12
	v_readfirstlane_b32 s13, v13
	v_readfirstlane_b32 s14, v14
	v_readfirstlane_b32 s15, v15
	v_readfirstlane_b32 s16, v16
	v_readfirstlane_b32 s17, v17
	v_readfirstlane_b32 s18, v18
	v_readfirstlane_b32 s19, v19
	v_readfirstlane_b32 s20, v20
	v_readfirstlane_b32 s21, v21
	v_readfirstlane_b32 s22, v22
	v_readfirstlane_b32 s23, v23
	v_readfirstlane_b32 s24, v24
	v_readfirstlane_b32 s25, v25
	v_readfirstlane_b32 s26, v26
	v_readfirstlane_b32 s27, v27
	v_readfirstlane_b32 s28, v28
	v_readfirstlane_b32 s29, v29
	v_readfirstlane_b32 s30, v30
	v_readfirstlane_b32 s34, v31
	v_readfirstlane_b32 s35, v32
	v_readfirstlane_b32 s36, v33
	v_readfirstlane_b32 s37, v34
	v_readfirstlane_b32 s38, v35
	v_readfirstlane_b32 s39, v36
	v_readfirstlane_b32 s40, v37
	v_readfirstlane_b32 s41, v38
	v_readfirstlane_b32 s42, v39
	v_readfirstlane_b32 s43, v40
	v_readfirstlane_b32 s44, v41
	v_readfirstlane_b32 s45, v42
	v_readfirstlane_b32 s46, v43
	v_readfirstlane_b32 s47, v44
	v_readfirstlane_b32 s48, v45
	v_readfirstlane_b32 s49, v46
	v_readfirstlane_b32 s50, v47
	v_readfirstlane_b32 s51, v48
	v_readfirstlane_b32 s52, v49
	v_readfirstlane_b32 s53, v50
	v_readfirstlane_b32 s54, v51
	v_readfirstlane_b32 s55, v52
	v_readfirstlane_b32 s56, v53
	s_waitcnt vmcnt(0)
	s_branch .Lband_exit

.Lfox_keep5:
	s_waitcnt vmcnt(0)
	v_pk_fma_f32 v[154:155], v[154:155], v[192:193], v[204:205] op_sel_hi:[1,0,0]
	v_exp_f32_e32 v154, v154
	v_exp_f32_e32 v155, v155
	v_pk_fma_f32 v[156:157], v[156:157], v[192:193], v[204:205] op_sel_hi:[1,0,0]
	v_exp_f32_e32 v156, v156
	v_exp_f32_e32 v157, v157
	v_pk_fma_f32 v[158:159], v[158:159], v[192:193], v[204:205] op_sel_hi:[1,0,0]
	v_exp_f32_e32 v158, v158
	v_exp_f32_e32 v159, v159
	v_pk_fma_f32 v[160:161], v[160:161], v[192:193], v[204:205] op_sel_hi:[1,0,0]
	v_exp_f32_e32 v160, v160
	v_exp_f32_e32 v161, v161
	v_pk_fma_f32 v[162:163], v[162:163], v[192:193], v[204:205] op_sel_hi:[1,0,0]
	v_exp_f32_e32 v162, v162
	v_exp_f32_e32 v163, v163
	v_pk_fma_f32 v[164:165], v[164:165], v[192:193], v[204:205] op_sel_hi:[1,0,0]
	v_exp_f32_e32 v164, v164
	v_exp_f32_e32 v165, v165
	v_pk_fma_f32 v[166:167], v[166:167], v[192:193], v[204:205] op_sel_hi:[1,0,0]
	v_exp_f32_e32 v166, v166
	v_exp_f32_e32 v167, v167
	v_pk_fma_f32 v[168:169], v[168:169], v[192:193], v[204:205] op_sel_hi:[1,0,0]
	v_exp_f32_e32 v168, v168
	v_exp_f32_e32 v169, v169
	v_pk_add_f32 v[184:185], v[154:155], v[156:157]
	v_pk_add_f32 v[186:187], v[158:159], v[160:161]
	v_pk_add_f32 v[184:185], v[184:185], v[162:163]
	v_pk_add_f32 v[186:187], v[186:187], v[164:165]
	v_pk_add_f32 v[184:185], v[184:185], v[166:167]
	v_pk_add_f32 v[186:187], v[186:187], v[168:169]
	v_pk_add_f32 v[184:185], v[184:185], v[186:187]
	v_add_f32_e32 v183, v184, v185
	v_add_f32_e32 v202, v202, v183
	v_cvt_pk_bf16_f32 v154, v154, v155
	v_cvt_pk_bf16_f32 v155, v156, v157
	v_cvt_pk_bf16_f32 v156, v158, v159
	v_cvt_pk_bf16_f32 v157, v160, v161
	v_cvt_pk_bf16_f32 v158, v162, v163
	v_cvt_pk_bf16_f32 v159, v164, v165
	v_cvt_pk_bf16_f32 v160, v166, v167
	v_cvt_pk_bf16_f32 v161, v168, v169
	s_nop 1
	v_mfma_f32_32x32x16_bf16 v[106:121], v[22:25], v[154:157], v[106:121]
	v_mfma_f32_32x32x16_bf16 v[122:137], v[30:33], v[154:157], v[122:137]
	v_mfma_f32_32x32x16_bf16 v[106:121], v[26:29], v[158:161], v[106:121]
	v_mfma_f32_32x32x16_bf16 v[122:137], v[34:37], v[158:161], v[122:137]
	s_nop 7
	s_nop 7
	v_mov_b32_e32 v184, v198
	s_nop 1
	v_permlane32_swap_b32_e32 v184, v198
	v_add_f32_e32 v198, v198, v184
	v_rcp_f32_e32 v186, v198
	s_nop 0
	v_fma_f32 v184, -v198, v186, 1.0
	v_fma_f32 v186, v186, v184, v186
	v_pk_mul_f32 v[74:75], v[74:75], v[186:187] op_sel_hi:[1,0]
	v_pk_mul_f32 v[76:77], v[76:77], v[186:187] op_sel_hi:[1,0]
	v_pk_mul_f32 v[78:79], v[78:79], v[186:187] op_sel_hi:[1,0]
	v_pk_mul_f32 v[80:81], v[80:81], v[186:187] op_sel_hi:[1,0]
	v_pk_mul_f32 v[82:83], v[82:83], v[186:187] op_sel_hi:[1,0]
	v_pk_mul_f32 v[84:85], v[84:85], v[186:187] op_sel_hi:[1,0]
	v_pk_mul_f32 v[86:87], v[86:87], v[186:187] op_sel_hi:[1,0]
	v_pk_mul_f32 v[88:89], v[88:89], v[186:187] op_sel_hi:[1,0]
	v_pk_mul_f32 v[90:91], v[90:91], v[186:187] op_sel_hi:[1,0]
	v_pk_mul_f32 v[92:93], v[92:93], v[186:187] op_sel_hi:[1,0]
	v_pk_mul_f32 v[94:95], v[94:95], v[186:187] op_sel_hi:[1,0]
	v_pk_mul_f32 v[96:97], v[96:97], v[186:187] op_sel_hi:[1,0]
	v_pk_mul_f32 v[98:99], v[98:99], v[186:187] op_sel_hi:[1,0]
	v_pk_mul_f32 v[100:101], v[100:101], v[186:187] op_sel_hi:[1,0]
	v_pk_mul_f32 v[102:103], v[102:103], v[186:187] op_sel_hi:[1,0]
	v_pk_mul_f32 v[104:105], v[104:105], v[186:187] op_sel_hi:[1,0]
	v_lshl_add_u32 v205, v196, 3, v205
	v_cvt_pk_bf16_f32 v74, v74, v75
	v_cvt_pk_bf16_f32 v75, v76, v77
	v_cvt_pk_bf16_f32 v76, v78, v79
	v_cvt_pk_bf16_f32 v77, v80, v81
	s_nop 1
	v_permlane32_swap_b32_e32 v74, v76
	v_permlane32_swap_b32_e32 v75, v77
	global_store_dwordx4 v205, v[74:77], s[12:13]
	v_cvt_pk_bf16_f32 v82, v82, v83
	v_cvt_pk_bf16_f32 v83, v84, v85
	v_cvt_pk_bf16_f32 v84, v86, v87
	v_cvt_pk_bf16_f32 v85, v88, v89
	s_nop 1
	v_permlane32_swap_b32_e32 v82, v84
	v_permlane32_swap_b32_e32 v83, v85
	global_store_dwordx4 v205, v[82:85], s[12:13] offset:32
	v_cvt_pk_bf16_f32 v90, v90, v91
	v_cvt_pk_bf16_f32 v91, v92, v93
	v_cvt_pk_bf16_f32 v92, v94, v95
	v_cvt_pk_bf16_f32 v93, v96, v97
	s_nop 1
	v_permlane32_swap_b32_e32 v90, v92
	v_permlane32_swap_b32_e32 v91, v93
	global_store_dwordx4 v205, v[90:93], s[12:13] offset:64
	v_cvt_pk_bf16_f32 v98, v98, v99
	v_cvt_pk_bf16_f32 v99, v100, v101
	v_cvt_pk_bf16_f32 v100, v102, v103
	v_cvt_pk_bf16_f32 v101, v104, v105
	s_nop 1
	v_permlane32_swap_b32_e32 v98, v100
	v_permlane32_swap_b32_e32 v99, v101
	global_store_dwordx4 v205, v[98:101], s[12:13] offset:96
	v_mov_b32_e32 v184, v202
	s_nop 1
	v_permlane32_swap_b32_e32 v184, v202
	v_add_f32_e32 v202, v202, v184
	v_rcp_f32_e32 v186, v202
	s_nop 0
	v_fma_f32 v184, -v202, v186, 1.0
	v_fma_f32 v186, v186, v184, v186
	v_pk_mul_f32 v[106:107], v[106:107], v[186:187] op_sel_hi:[1,0]
	v_pk_mul_f32 v[108:109], v[108:109], v[186:187] op_sel_hi:[1,0]
	v_pk_mul_f32 v[110:111], v[110:111], v[186:187] op_sel_hi:[1,0]
	v_pk_mul_f32 v[112:113], v[112:113], v[186:187] op_sel_hi:[1,0]
	v_pk_mul_f32 v[114:115], v[114:115], v[186:187] op_sel_hi:[1,0]
	v_pk_mul_f32 v[116:117], v[116:117], v[186:187] op_sel_hi:[1,0]
	v_pk_mul_f32 v[118:119], v[118:119], v[186:187] op_sel_hi:[1,0]
	v_pk_mul_f32 v[120:121], v[120:121], v[186:187] op_sel_hi:[1,0]
	v_pk_mul_f32 v[122:123], v[122:123], v[186:187] op_sel_hi:[1,0]
	v_pk_mul_f32 v[124:125], v[124:125], v[186:187] op_sel_hi:[1,0]
	v_pk_mul_f32 v[126:127], v[126:127], v[186:187] op_sel_hi:[1,0]
	v_pk_mul_f32 v[128:129], v[128:129], v[186:187] op_sel_hi:[1,0]
	v_pk_mul_f32 v[130:131], v[130:131], v[186:187] op_sel_hi:[1,0]
	v_pk_mul_f32 v[132:133], v[132:133], v[186:187] op_sel_hi:[1,0]
	v_pk_mul_f32 v[134:135], v[134:135], v[186:187] op_sel_hi:[1,0]
	v_pk_mul_f32 v[136:137], v[136:137], v[186:187] op_sel_hi:[1,0]
	v_lshl_add_u32 v206, v196, 3, v206
	v_cvt_pk_bf16_f32 v106, v106, v107
	v_cvt_pk_bf16_f32 v107, v108, v109
	v_cvt_pk_bf16_f32 v108, v110, v111
	v_cvt_pk_bf16_f32 v109, v112, v113
	s_nop 1
	v_permlane32_swap_b32_e32 v106, v108
	v_permlane32_swap_b32_e32 v107, v109
	global_store_dwordx4 v206, v[106:109], s[12:13]
	v_cvt_pk_bf16_f32 v114, v114, v115
	v_cvt_pk_bf16_f32 v115, v116, v117
	v_cvt_pk_bf16_f32 v116, v118, v119
	v_cvt_pk_bf16_f32 v117, v120, v121
	s_nop 1
	v_permlane32_swap_b32_e32 v114, v116
	v_permlane32_swap_b32_e32 v115, v117
	global_store_dwordx4 v206, v[114:117], s[12:13] offset:32
	v_cvt_pk_bf16_f32 v122, v122, v123
	v_cvt_pk_bf16_f32 v123, v124, v125
	v_cvt_pk_bf16_f32 v124, v126, v127
	v_cvt_pk_bf16_f32 v125, v128, v129
	s_nop 1
	v_permlane32_swap_b32_e32 v122, v124
	v_permlane32_swap_b32_e32 v123, v125
	global_store_dwordx4 v206, v[122:125], s[12:13] offset:64
	v_cvt_pk_bf16_f32 v130, v130, v131
	v_cvt_pk_bf16_f32 v131, v132, v133
	v_cvt_pk_bf16_f32 v132, v134, v135
	v_cvt_pk_bf16_f32 v133, v136, v137
	s_nop 1
	v_permlane32_swap_b32_e32 v130, v132
	v_permlane32_swap_b32_e32 v131, v133
	global_store_dwordx4 v206, v[130:133], s[12:13] offset:96
	s_waitcnt vmcnt(0)
	s_add_i32 s22, s22, s68
	s_cmpk_lt_i32 s22, 0x800
	s_cbranch_scc1 .Lfox_outer
	v_lshlrev_b32_e32 v2, 2, v220
	v_add_u32_e32 v3, 0x10000, v2
	ds_read_b32 v146, v2 offset:0
	ds_read_b32 v147, v2 offset:2048
	ds_read_b32 v148, v2 offset:4096
	ds_read_b32 v149, v2 offset:6144
	ds_read_b32 v150, v2 offset:8192
	ds_read_b32 v151, v2 offset:10240
	ds_read_b32 v152, v2 offset:12288
	ds_read_b32 v153, v2 offset:14336
	ds_read_b32 v154, v2 offset:16384
	ds_read_b32 v155, v2 offset:18432
	ds_read_b32 v156, v2 offset:20480
	ds_read_b32 v157, v2 offset:22528
	ds_read_b32 v158, v2 offset:24576
	ds_read_b32 v159, v2 offset:26624
	ds_read_b32 v160, v2 offset:28672
	ds_read_b32 v161, v2 offset:30720
	ds_read_b32 v162, v2 offset:32768
	ds_read_b32 v163, v2 offset:34816
	ds_read_b32 v164, v2 offset:36864
	ds_read_b32 v165, v2 offset:38912
	ds_read_b32 v166, v2 offset:40960
	ds_read_b32 v167, v2 offset:43008
	ds_read_b32 v168, v2 offset:45056
	ds_read_b32 v169, v2 offset:47104
	ds_read_b32 v170, v2 offset:49152
	ds_read_b32 v183, v2 offset:51200
	ds_read_b32 v184, v2 offset:53248
	ds_read_b32 v185, v2 offset:55296
	ds_read_b32 v186, v2 offset:57344
	ds_read_b32 v187, v2 offset:59392
	ds_read_b32 v188, v2 offset:61440
	ds_read_b32 v189, v2 offset:63488
	ds_read_b32 v190, v3 offset:0
	ds_read_b32 v191, v3 offset:2048
	ds_read_b32 v192, v3 offset:4096
	ds_read_b32 v193, v3 offset:6144
	ds_read_b32 v194, v3 offset:8192
	ds_read_b32 v195, v3 offset:10240
	ds_read_b32 v196, v3 offset:12288
	ds_read_b32 v197, v3 offset:14336
	ds_read_b32 v198, v3 offset:16384
	ds_read_b32 v199, v3 offset:18432
	ds_read_b32 v200, v3 offset:20480
	ds_read_b32 v201, v3 offset:22528
	ds_read_b32 v202, v3 offset:24576
	ds_read_b32 v203, v3 offset:26624
	ds_read_b32 v204, v3 offset:28672
	ds_read_b32 v205, v3 offset:30720
	ds_read_b32 v206, v3 offset:32768
	ds_read_b32 v207, v3 offset:34816
	ds_read_b32 v208, v3 offset:36864
	ds_read_b32 v209, v3 offset:38912
	ds_read_b32 v210, v3 offset:40960
	ds_read_b32 v211, v3 offset:43008
	ds_read_b32 v212, v3 offset:45056
	ds_read_b32 v213, v3 offset:47104
	ds_read_b32 v214, v3 offset:49152
	ds_read_b32 v215, v3 offset:51200
	ds_read_b32 v216, v3 offset:53248
	v_lshrrev_b32_e32 v2, 6, v220
	v_lshlrev_b32_e32 v2, 8, v2
	v_add_u32_e32 v2, 0x1d800, v2
	ds_read_b32 v4, v2 offset:0
	ds_read_b32 v5, v2 offset:4
	ds_read_b32 v6, v2 offset:8
	ds_read_b32 v7, v2 offset:12
	ds_read_b32 v8, v2 offset:16
	ds_read_b32 v9, v2 offset:20
	ds_read_b32 v10, v2 offset:24
	ds_read_b32 v11, v2 offset:28
	ds_read_b32 v12, v2 offset:32
	ds_read_b32 v13, v2 offset:36
	ds_read_b32 v14, v2 offset:40
	ds_read_b32 v15, v2 offset:44
	ds_read_b32 v16, v2 offset:48
	ds_read_b32 v17, v2 offset:52
	ds_read_b32 v18, v2 offset:56
	ds_read_b32 v19, v2 offset:60
	ds_read_b32 v20, v2 offset:64
	ds_read_b32 v21, v2 offset:68
	ds_read_b32 v22, v2 offset:72
	ds_read_b32 v23, v2 offset:76
	ds_read_b32 v24, v2 offset:80
	ds_read_b32 v25, v2 offset:84
	ds_read_b32 v26, v2 offset:88
	ds_read_b32 v27, v2 offset:92
	ds_read_b32 v28, v2 offset:96
	ds_read_b32 v29, v2 offset:100
	ds_read_b32 v30, v2 offset:104
	ds_read_b32 v31, v2 offset:108
	ds_read_b32 v32, v2 offset:112
	ds_read_b32 v33, v2 offset:116
	ds_read_b32 v34, v2 offset:120
	ds_read_b32 v35, v2 offset:124
	ds_read_b32 v36, v2 offset:128
	ds_read_b32 v37, v2 offset:132
	ds_read_b32 v38, v2 offset:136
	ds_read_b32 v39, v2 offset:140
	ds_read_b32 v40, v2 offset:144
	ds_read_b32 v41, v2 offset:148
	ds_read_b32 v42, v2 offset:152
	ds_read_b32 v43, v2 offset:156
	ds_read_b32 v44, v2 offset:160
	ds_read_b32 v45, v2 offset:164
	s_waitcnt lgkmcnt(0)
	v_readfirstlane_b32 s2, v4
	v_readfirstlane_b32 s3, v5
	v_readfirstlane_b32 s4, v6
	v_readfirstlane_b32 s5, v7
	v_readfirstlane_b32 s6, v8
	v_readfirstlane_b32 s7, v9
	v_readfirstlane_b32 s8, v10
	v_readfirstlane_b32 s9, v11
	v_readfirstlane_b32 s10, v12
	v_readfirstlane_b32 s11, v13
	v_readfirstlane_b32 s12, v14
	v_readfirstlane_b32 s13, v15
	v_readfirstlane_b32 s14, v16
	v_readfirstlane_b32 s15, v17
	v_readfirstlane_b32 s16, v18
	v_readfirstlane_b32 s17, v19
	v_readfirstlane_b32 s18, v20
	v_readfirstlane_b32 s19, v21
	v_readfirstlane_b32 s20, v22
	v_readfirstlane_b32 s21, v23
	v_readfirstlane_b32 s22, v24
	v_readfirstlane_b32 s23, v25
	v_readfirstlane_b32 s24, v26
	v_readfirstlane_b32 s25, v27
	v_readfirstlane_b32 s26, v28
	v_readfirstlane_b32 s27, v29
	v_readfirstlane_b32 s28, v30
	v_readfirstlane_b32 s29, v31
	v_readfirstlane_b32 s30, v32
	v_readfirstlane_b32 s31, v33
	v_readfirstlane_b32 s34, v34
	v_readfirstlane_b32 s35, v35
	v_readfirstlane_b32 s36, v36
	v_readfirstlane_b32 s37, v37
	v_readfirstlane_b32 s38, v38
	v_readfirstlane_b32 s39, v39
	v_readfirstlane_b32 s40, v40
	v_readfirstlane_b32 s41, v41
	v_readfirstlane_b32 s42, v42
	v_readfirstlane_b32 s43, v43
	v_readfirstlane_b32 s44, v44
	v_readfirstlane_b32 s45, v45
